# final RMSNorm loop: all row loads issued together, gain vector hoisted out of the loop, one wait per row
# speedup vs baseline: 1.0086x; 1.0004x over previous
.LBB0_12:
	s_cmp_eq_u32 s82, 46
	s_mov_b64 s[4:5], -1
	s_cbranch_scc0 .LBB0_17
	v_mov_b32_e32 v0, v167
	v_readlane_b32 s2, v252, 2
	v_ashrrev_i32_e32 v2, 6, v0
	s_nop 0
	v_add_u32_e32 v18, s2, v2
	v_cmp_gt_i32_e32 vcc, s84, v18
	s_and_saveexec_b64 s[4:5], vcc
	s_movk_i32 s16, 0x41ff
	s_mov_b32 s17, 0x800000
	v_readlane_b32 s18, v252, 3
	s_cbranch_execz .LBB0_16
	v_lshlrev_b32_e32 v0, 2, v0
	v_and_b32_e32 v2, 0xfc, v0
	s_movk_i32 s2, 0x80
	v_readlane_b32 s8, v252, 34
	v_bitop3_b32 v26, v0, s2, v216 bitop3:0x6c
	v_bitop3_b32 v27, v0, 64, v216 bitop3:0x6c
	v_bitop3_b32 v28, v0, 32, v216 bitop3:0x6c
	v_bitop3_b32 v29, v0, 16, v216 bitop3:0x6c
	v_bitop3_b32 v30, v0, 8, v216 bitop3:0x6c
	v_bitop3_b32 v31, v0, 4, v216 bitop3:0x6c
	v_lshlrev_b32_e32 v0, 2, v2
	v_readlane_b32 s10, v252, 36
	v_readlane_b32 s11, v252, 37
	s_waitcnt vmcnt(0)
	v_lshl_add_u64 v[22:23], s[76:77], 0, v[0:1]
	s_mov_b64 s[6:7], 0
	v_lshl_add_u64 v[20:21], s[10:11], 0, v[0:1]
	v_readlane_b32 s9, v252, 35
	v_readlane_b32 s12, v252, 38
	v_readlane_b32 s13, v252, 39
	v_readlane_b32 s14, v252, 40
	v_readlane_b32 s15, v252, 41
	global_load_dwordx4 v[40:43], v[20:21], off
	global_load_dwordx4 v[44:47], v[20:21], off offset:1024
	global_load_dwordx4 v[48:51], v[20:21], off offset:2048
	global_load_dwordx4 v[52:55], v[20:21], off offset:3072
.LBB0_15:
	v_ashrrev_i32_e32 v19, 31, v18
	v_lshlrev_b64 v[2:3], 12, v[18:19]
	v_lshl_add_u64 v[24:25], v[22:23], 0, v[2:3]
	global_load_dwordx4 v[6:9], v[24:25], off
	global_load_dwordx4 v[2:5], v[24:25], off offset:1024
	global_load_dwordx4 v[14:17], v[24:25], off offset:2048
	global_load_dwordx4 v[10:13], v[24:25], off offset:3072
	v_add_u32_e32 v18, s18, v18
	s_waitcnt vmcnt(0)
	v_pk_mul_f32 v[32:33], v[6:7], v[6:7]
	s_nop 0
	v_pk_fma_f32 v[32:33], v[8:9], v[8:9], v[32:33]
	s_nop 0
	v_pk_fma_f32 v[32:33], v[2:3], v[2:3], v[32:33]
	s_nop 0
	v_pk_fma_f32 v[32:33], v[4:5], v[4:5], v[32:33]
	s_nop 0
	v_pk_fma_f32 v[32:33], v[14:15], v[14:15], v[32:33]
	s_nop 0
	v_pk_fma_f32 v[32:33], v[16:17], v[16:17], v[32:33]
	s_nop 0
	v_pk_fma_f32 v[32:33], v[10:11], v[10:11], v[32:33]
	s_nop 0
	v_pk_fma_f32 v[32:33], v[12:13], v[12:13], v[32:33]
	s_nop 0
	v_add_f32_e32 v0, v32, v33
	ds_bpermute_b32 v19, v26, v0
	s_waitcnt lgkmcnt(0)
	v_add_f32_e32 v0, v0, v19
	ds_bpermute_b32 v19, v27, v0
	s_waitcnt lgkmcnt(0)
	v_add_f32_e32 v0, v0, v19
	ds_bpermute_b32 v19, v28, v0
	s_waitcnt lgkmcnt(0)
	v_add_f32_e32 v0, v0, v19
	ds_bpermute_b32 v19, v29, v0
	s_waitcnt lgkmcnt(0)
	v_add_f32_e32 v0, v0, v19
	ds_bpermute_b32 v19, v30, v0
	s_waitcnt lgkmcnt(0)
	v_add_f32_e32 v0, v0, v19
	ds_bpermute_b32 v19, v31, v0
	s_waitcnt lgkmcnt(0)
	v_add_f32_e32 v0, v0, v19
	v_fmamk_f32 v0, v0, 0x3a800000, v166
	v_cmp_gt_f32_e32 vcc, s17, v0
	v_mul_f32_e32 v19, 0x4b800000, v0
	s_nop 0
	v_cndmask_b32_e32 v0, v0, v19, vcc
	v_rsq_f32_e32 v0, v0
	s_nop 0
	v_mul_f32_e32 v19, 0x45800000, v0
	v_cndmask_b32_e32 v0, v0, v19, vcc
	s_nop 0
	v_pk_mul_f32 v[6:7], v[6:7], v[0:1] op_sel_hi:[1,0]
	v_pk_mul_f32 v[8:9], v[8:9], v[0:1] op_sel_hi:[1,0]
	v_pk_mul_f32 v[2:3], v[2:3], v[0:1] op_sel_hi:[1,0]
	v_pk_mul_f32 v[4:5], v[4:5], v[0:1] op_sel_hi:[1,0]
	v_pk_mul_f32 v[14:15], v[14:15], v[0:1] op_sel_hi:[1,0]
	v_pk_mul_f32 v[16:17], v[16:17], v[0:1] op_sel_hi:[1,0]
	v_pk_mul_f32 v[10:11], v[10:11], v[0:1] op_sel_hi:[1,0]
	v_pk_mul_f32 v[12:13], v[12:13], v[0:1] op_sel_hi:[1,0]
	s_nop 0
	v_pk_mul_f32 v[6:7], v[40:41], v[6:7]
	v_pk_mul_f32 v[8:9], v[42:43], v[8:9]
	v_pk_mul_f32 v[2:3], v[44:45], v[2:3]
	v_pk_mul_f32 v[4:5], v[46:47], v[4:5]
	v_pk_mul_f32 v[14:15], v[48:49], v[14:15]
	v_pk_mul_f32 v[16:17], v[50:51], v[16:17]
	v_pk_mul_f32 v[10:11], v[52:53], v[10:11]
	v_pk_mul_f32 v[12:13], v[54:55], v[12:13]
	s_nop 0
	global_store_dwordx4 v[24:25], v[6:9], off
	global_store_dwordx4 v[24:25], v[2:5], off offset:1024
	global_store_dwordx4 v[24:25], v[14:17], off offset:2048
	global_store_dwordx4 v[24:25], v[10:13], off offset:3072
	v_cmp_lt_i32_e32 vcc, s16, v18
	s_or_b64 s[6:7], vcc, s[6:7]
	s_andn2_b64 exec, exec, s[6:7]
	s_cbranch_execnz .LBB0_15
